# prep: x->bf16 row loop with next-row loads in flight (scalar row index, counted vmcnt); sample V-cache transpose lane remap (8 rows x 32B per load); barrier census loads issued together
# speedup vs baseline: 1.0089x; 1.0089x over previous
.LBB0_253:
	s_waitcnt vmcnt(3)
	v_ashrrev_i32_e32 v0, 6, v206
	s_waitcnt vmcnt(2)
	v_and_b32_e32 v4, 63, v206
	v_cmp_lt_i32_e32 vcc, 5, v0
	s_and_saveexec_b64 s[2:3], vcc
	s_xor_b64 s[2:3], exec, s[2:3]
	s_cbranch_execz .LBB0_301
	v_lshl_add_u32 v0, s90, 7, v206
	v_add_u32_e32 v6, 0xfffffe80, v0
	s_lshl_b32 s4, s74, 7
	v_cmp_gt_i32_e32 vcc, s31, v6
	v_and_b32_e32 v2, 0x7f, v206
	v_ashrrev_i32_e32 v7, 31, v6
	s_and_saveexec_b64 s[6:7], vcc
	s_cbranch_execz .LBB0_271
	s_load_dwordx4 s[52:55], s[0:1], 0x10
	s_add_u32 s8, s72, 0xe9c8000
	s_addc_u32 s9, s73, 0
	s_waitcnt lgkmcnt(0)
	s_add_u32 s10, s72, 0xec48000
	s_addc_u32 s11, s73, 0
	s_lshl_b32 s12, s74, 10
	s_ashr_i32 s13, s12, 31
	v_lshl_add_u64 v[0:1], v[6:7], 2, s[52:53]
	s_lshl_b64 s[14:15], s[12:13], 2
	s_lshl_b32 s5, s74, 8
	s_lshl_b32 s13, s74, 9
	s_mov_b64 s[26:27], 0
	v_mov_b32_e32 v3, v6
	v_bfe_u32 v44, v6, 3, 3
	v_lshrrev_b32_e32 v45, 7, v6
	v_and_b32_e32 v45, 0x78, v45
	v_or_b32_e32 v44, v44, v45
	v_lshrrev_b32_e32 v45, 3, v6
	v_and_b32_e32 v45, 0x78, v45
	v_and_or_b32 v45, v6, 7, v45
	s_branch .LBB0_257

.LBB0_257:
	v_add_u32_e32 v25, s4, v3
	v_cmp_gt_i32_e64 s[48:49], s31, v25
	v_add_u32_e32 v21, s5, v3
	v_cmp_gt_i32_e64 s[46:47], s31, v21
	s_waitcnt vmcnt(1)
	v_cndmask_b32_e64 v8, v3, v25, s[48:49]
	v_ashrrev_i32_e32 v9, 31, v8
	v_bfe_u32 v5, v8, 14, 5
	v_lshl_add_u64 v[10:11], v[8:9], 2, s[52:53]
	v_ashrrev_i32_e32 v9, 14, v8
	s_waitcnt vmcnt(0)
	v_mov_b32_e32 v12, v44
	v_and_or_b32 v5, v9, s88, v5
	global_load_dword v26, v[10:11], off
	v_lshl_or_b32 v10, v5, 7, v12
	v_ashrrev_i32_e32 v11, 31, v10
	v_lshlrev_b64 v[10:11], 9, v[10:11]
	v_lshrrev_b32_e32 v5, 5, v8
	v_lshl_add_u64 v[10:11], s[54:55], 0, v[10:11]
	v_lshlrev_b32_e32 v8, 2, v45
	v_mov_b32_e32 v9, v20
	v_lshl_add_u64 v[8:9], v[10:11], 0, v[8:9]
	global_load_dword v28, v[8:9], off
	v_cndmask_b32_e64 v8, v3, v21, s[46:47]
	v_ashrrev_i32_e32 v9, 31, v8
	v_bfe_u32 v5, v8, 14, 5
	v_lshl_add_u64 v[10:11], v[8:9], 2, s[52:53]
	v_ashrrev_i32_e32 v9, 14, v8
	v_mov_b32_e32 v12, v44
	v_and_or_b32 v5, v9, s88, v5
	global_load_dword v22, v[10:11], off
	v_lshl_or_b32 v10, v5, 7, v12
	v_ashrrev_i32_e32 v11, 31, v10
	v_lshlrev_b64 v[10:11], 9, v[10:11]
	v_lshrrev_b32_e32 v5, 5, v8
	s_mul_i32 s16, s74, 0x180
	v_lshl_add_u64 v[10:11], s[54:55], 0, v[10:11]
	v_lshlrev_b32_e32 v8, 2, v45
	v_mov_b32_e32 v9, v20
	v_add_u32_e32 v17, s16, v3
	v_lshl_add_u64 v[8:9], v[10:11], 0, v[8:9]
	v_cmp_gt_i32_e64 s[44:45], s31, v17
	global_load_dword v24, v[8:9], off
	v_add_u32_e32 v13, s13, v3
	v_cndmask_b32_e64 v8, v3, v17, s[44:45]
	v_ashrrev_i32_e32 v9, 31, v8
	v_bfe_u32 v5, v8, 14, 5
	v_lshl_add_u64 v[10:11], v[8:9], 2, s[52:53]
	v_ashrrev_i32_e32 v9, 14, v8
	v_mov_b32_e32 v12, v44
	v_and_or_b32 v5, v9, s88, v5
	global_load_dword v18, v[10:11], off
	v_lshl_or_b32 v10, v5, 7, v12
	v_ashrrev_i32_e32 v11, 31, v10
	v_lshlrev_b64 v[10:11], 9, v[10:11]
	v_lshrrev_b32_e32 v5, 5, v8
	v_lshl_add_u64 v[10:11], s[54:55], 0, v[10:11]
	v_lshlrev_b32_e32 v8, 2, v45
	v_mov_b32_e32 v9, v20
	v_lshl_add_u64 v[8:9], v[10:11], 0, v[8:9]
	v_cmp_gt_i32_e64 s[42:43], s31, v13
	global_load_dword v19, v[8:9], off
	s_mul_i32 s16, s74, 0x280
	v_cndmask_b32_e64 v8, v3, v13, s[42:43]
	v_ashrrev_i32_e32 v9, 31, v8
	v_bfe_u32 v5, v8, 14, 5
	v_lshl_add_u64 v[10:11], v[8:9], 2, s[52:53]
	v_ashrrev_i32_e32 v9, 14, v8
	v_mov_b32_e32 v12, v44
	v_and_or_b32 v5, v9, s88, v5
	global_load_dword v14, v[10:11], off
	v_lshl_or_b32 v10, v5, 7, v12
	v_ashrrev_i32_e32 v11, 31, v10
	v_lshlrev_b64 v[10:11], 9, v[10:11]
	v_lshrrev_b32_e32 v5, 5, v8
	v_lshl_add_u64 v[10:11], s[54:55], 0, v[10:11]
	v_lshlrev_b32_e32 v8, 2, v45
	v_mov_b32_e32 v9, v20
	v_lshl_add_u64 v[8:9], v[10:11], 0, v[8:9]
	v_add_u32_e32 v10, s16, v3
	v_cmp_gt_i32_e64 s[40:41], s31, v10
	global_load_dword v15, v[8:9], off
	s_mul_i32 s16, s74, 0x300
	v_cndmask_b32_e64 v8, v3, v10, s[40:41]
	v_ashrrev_i32_e32 v9, 31, v8
	v_bfe_u32 v5, v8, 14, 5
	v_lshl_add_u64 v[30:31], v[8:9], 2, s[52:53]
	v_ashrrev_i32_e32 v9, 14, v8
	v_mov_b32_e32 v12, v44
	v_and_or_b32 v5, v9, s88, v5
	global_load_dword v11, v[30:31], off
	v_lshl_or_b32 v30, v5, 7, v12
	v_ashrrev_i32_e32 v31, 31, v30
	v_lshlrev_b64 v[30:31], 9, v[30:31]
	v_lshrrev_b32_e32 v5, 5, v8
	v_lshl_add_u64 v[30:31], s[54:55], 0, v[30:31]
	v_lshlrev_b32_e32 v8, 2, v45
	v_mov_b32_e32 v9, v20
	v_lshl_add_u64 v[8:9], v[30:31], 0, v[8:9]
	global_load_dword v12, v[8:9], off
	v_add_u32_e32 v8, s16, v3
	v_cmp_gt_i32_e64 s[38:39], s31, v8
	s_mul_i32 s16, s74, 0x380
	v_bfe_u32 v40, v3, 14, 5
	v_cndmask_b32_e64 v30, v3, v8, s[38:39]
	v_bfe_u32 v5, v30, 14, 5
	v_ashrrev_i32_e32 v31, 31, v30
	v_ashrrev_i32_e32 v23, 14, v30
	v_mov_b32_e32 v16, v44
	v_lshl_add_u64 v[32:33], v[30:31], 2, s[52:53]
	v_and_or_b32 v5, v23, s88, v5
	global_load_dword v9, v[32:33], off
	v_lshl_or_b32 v32, v5, 7, v16
	v_add_u32_e32 v5, s16, v3
	v_cmp_gt_i32_e32 vcc, s31, v5
	v_lshrrev_b32_e32 v23, 5, v30
	v_mov_b32_e32 v37, v20
	v_cndmask_b32_e32 v30, v3, v5, vcc
	v_bfe_u32 v16, v30, 14, 5
	v_ashrrev_i32_e32 v29, 14, v30
	v_mov_b32_e32 v27, v44
	v_and_or_b32 v16, v29, s88, v16
	v_lshl_or_b32 v34, v16, 7, v27
	v_ashrrev_i32_e32 v35, 31, v34
	v_lshrrev_b32_e32 v16, 5, v30
	v_lshlrev_b64 v[34:35], 9, v[34:35]
	v_lshlrev_b32_e32 v36, 2, v45
	v_ashrrev_i32_e32 v16, 14, v3
	v_lshl_add_u64 v[34:35], s[54:55], 0, v[34:35]
	v_and_or_b32 v16, v16, s88, v40
	v_lshl_add_u64 v[34:35], v[34:35], 0, v[36:37]
	v_lshl_or_b32 v36, v16, 7, v44
	v_ashrrev_i32_e32 v37, 31, v36
	v_lshlrev_b64 v[36:37], 9, v[36:37]
	v_bfe_u32 v41, v3, 7, 7
	v_ashrrev_i32_e32 v33, 31, v32
	v_lshl_add_u64 v[36:37], s[54:55], 0, v[36:37]
	v_lshlrev_b32_e32 v38, 2, v45
	v_mov_b32_e32 v39, v20
	v_lshlrev_b64 v[32:33], 9, v[32:33]
	v_lshl_add_u64 v[36:37], v[36:37], 0, v[38:39]
	v_lshl_add_u64 v[32:33], s[54:55], 0, v[32:33]
	global_load_dword v27, v[0:1], off
	global_load_dword v16, v[34:35], off
	s_nop 0
	global_load_dword v36, v[36:37], off
	v_lshlrev_b32_e32 v34, 2, v45
	v_mov_b32_e32 v35, v20
	v_ashrrev_i32_e32 v31, 31, v30
	v_lshl_add_u64 v[32:33], v[32:33], 0, v[34:35]
	v_lshl_add_u64 v[30:31], v[30:31], 2, s[52:53]
	global_load_dword v29, v[32:33], off
	global_load_dword v23, v[30:31], off
	v_ashrrev_i32_e32 v30, 19, v3
	v_mul_hi_i32_i24_e32 v31, 0x140000, v30
	v_mul_i32_i24_e32 v30, 0x140000, v30
	s_waitcnt vmcnt(4)
	v_cvt_pk_bf16_f32 v37, v27, v20
	v_mad_u32_u24 v34, v40, s23, v41
	v_lshlrev_b32_e32 v27, 1, v2
	v_lshl_add_u64 v[32:33], s[8:9], 0, v[30:31]
	v_lshl_or_b32 v34, v34, 8, v27
	v_lshl_add_u64 v[32:33], v[32:33], 0, v[34:35]
	global_store_short v[32:33], v37, off
	v_lshl_or_b32 v32, v40, 7, v45
	v_mul_u32_u24_e32 v32, 0xa0, v32
	v_lshl_add_u64 v[30:31], s[10:11], 0, v[30:31]
	v_add_lshl_u32 v32, v32, v44, 1
	v_mov_b32_e32 v33, v20
	v_lshl_add_u64 v[30:31], v[30:31], 0, v[32:33]
	s_waitcnt vmcnt(3)
	v_cvt_pk_bf16_f32 v34, v36, v20
	global_store_short v[30:31], v34, off
	s_and_saveexec_b64 s[50:51], s[48:49]
	s_cbranch_execz .LBB0_264
	v_bfe_u32 v36, v25, 7, 7
	v_bfe_u32 v37, v25, 14, 5
	v_ashrrev_i32_e32 v25, 19, v25
	v_mul_hi_i32_i24_e32 v31, 0x140000, v25
	v_mul_i32_i24_e32 v30, 0x140000, v25
	v_cvt_pk_bf16_f32 v25, v26, v20
	v_mad_u32_u24 v26, v37, s23, v36
	v_lshl_add_u64 v[32:33], s[8:9], 0, v[30:31]
	v_lshl_or_b32 v34, v26, 8, v27
	v_mov_b32_e32 v35, v20
	v_lshl_or_b32 v26, v37, 7, v45
	v_lshl_add_u64 v[32:33], v[32:33], 0, v[34:35]
	v_mul_u32_u24_e32 v26, 0xa0, v26
	v_lshl_add_u64 v[30:31], s[10:11], 0, v[30:31]
	global_store_short v[32:33], v25, off
	v_add_lshl_u32 v32, v26, v44, 1
	v_mov_b32_e32 v33, v20
	v_lshl_add_u64 v[30:31], v[30:31], 0, v[32:33]
	v_cvt_pk_bf16_f32 v25, v28, v20
	global_store_short v[30:31], v25, off
	s_or_b64 exec, exec, s[50:51]
	s_and_saveexec_b64 s[48:49], s[46:47]
	s_cbranch_execnz .LBB0_265

.LBB0_260:
	v_bfe_u32 v21, v17, 7, 7
	v_bfe_u32 v22, v17, 14, 5
	v_ashrrev_i32_e32 v17, 19, v17
	v_mul_hi_i32_i24_e32 v25, 0x140000, v17
	v_mul_i32_i24_e32 v24, 0x140000, v17
	v_cvt_pk_bf16_f32 v17, v18, v20
	v_mad_u32_u24 v18, v22, s23, v21
	v_lshl_add_u64 v[30:31], s[8:9], 0, v[24:25]
	v_lshl_or_b32 v32, v18, 8, v27
	v_mov_b32_e32 v33, v20
	v_lshl_or_b32 v18, v22, 7, v45
	v_lshl_add_u64 v[30:31], v[30:31], 0, v[32:33]
	v_mul_u32_u24_e32 v18, 0xa0, v18
	v_lshl_add_u64 v[24:25], s[10:11], 0, v[24:25]
	global_store_short v[30:31], v17, off
	v_cvt_pk_bf16_f32 v17, v19, v20
	v_add_lshl_u32 v18, v18, v44, 1
	v_mov_b32_e32 v19, v20
	v_lshl_add_u64 v[18:19], v[24:25], 0, v[18:19]
	global_store_short v[18:19], v17, off
	s_or_b64 exec, exec, s[46:47]
	s_and_saveexec_b64 s[44:45], s[42:43]
	s_cbranch_execnz .LBB0_267

.LBB0_262:
	v_bfe_u32 v13, v10, 7, 7
	v_bfe_u32 v17, v10, 14, 5
	v_ashrrev_i32_e32 v10, 19, v10
	v_mul_hi_i32_i24_e32 v15, 0x140000, v10
	v_mul_i32_i24_e32 v14, 0x140000, v10
	v_mad_u32_u24 v10, v17, s23, v13
	v_lshl_add_u64 v[18:19], s[8:9], 0, v[14:15]
	v_cvt_pk_bf16_f32 v21, v11, v20
	v_lshl_or_b32 v10, v10, 8, v27
	v_mov_b32_e32 v11, v20
	v_lshl_add_u64 v[10:11], v[18:19], 0, v[10:11]
	global_store_short v[10:11], v21, off
	v_lshl_or_b32 v10, v17, 7, v45
	v_mul_u32_u24_e32 v10, 0xa0, v10
	v_lshl_add_u64 v[14:15], s[10:11], 0, v[14:15]
	v_add_lshl_u32 v10, v10, v44, 1
	v_mov_b32_e32 v11, v20
	v_lshl_add_u64 v[10:11], v[14:15], 0, v[10:11]
	v_cvt_pk_bf16_f32 v12, v12, v20
	global_store_short v[10:11], v12, off
	s_or_b64 exec, exec, s[42:43]
	s_and_saveexec_b64 s[40:41], s[38:39]
	s_cbranch_execnz .LBB0_269

.LBB0_265:
	v_bfe_u32 v25, v21, 7, 7
	v_bfe_u32 v26, v21, 14, 5
	v_ashrrev_i32_e32 v21, 19, v21
	v_mul_hi_i32_i24_e32 v31, 0x140000, v21
	v_mul_i32_i24_e32 v30, 0x140000, v21
	v_cvt_pk_bf16_f32 v21, v22, v20
	v_mad_u32_u24 v22, v26, s23, v25
	v_lshl_add_u64 v[32:33], s[8:9], 0, v[30:31]
	v_lshl_or_b32 v34, v22, 8, v27
	v_mov_b32_e32 v35, v20
	v_lshl_or_b32 v22, v26, 7, v45
	v_lshl_add_u64 v[32:33], v[32:33], 0, v[34:35]
	v_mul_u32_u24_e32 v22, 0xa0, v22
	v_lshl_add_u64 v[30:31], s[10:11], 0, v[30:31]
	global_store_short v[32:33], v21, off
	v_cvt_pk_bf16_f32 v21, v24, v20
	v_add_lshl_u32 v24, v22, v44, 1
	v_mov_b32_e32 v25, v20
	v_lshl_add_u64 v[24:25], v[30:31], 0, v[24:25]
	global_store_short v[24:25], v21, off
	s_or_b64 exec, exec, s[48:49]
	s_and_saveexec_b64 s[46:47], s[44:45]
	s_cbranch_execnz .LBB0_260

.LBB0_267:
	v_bfe_u32 v17, v13, 7, 7
	v_bfe_u32 v21, v13, 14, 5
	v_ashrrev_i32_e32 v13, 19, v13
	v_mul_hi_i32_i24_e32 v19, 0x140000, v13
	v_mul_i32_i24_e32 v18, 0x140000, v13
	v_cvt_pk_bf16_f32 v13, v14, v20
	v_mad_u32_u24 v14, v21, s23, v17
	v_lshl_add_u64 v[24:25], s[8:9], 0, v[18:19]
	v_lshl_or_b32 v30, v14, 8, v27
	v_mov_b32_e32 v31, v20
	v_lshl_or_b32 v14, v21, 7, v45
	v_lshl_add_u64 v[24:25], v[24:25], 0, v[30:31]
	v_mul_u32_u24_e32 v14, 0xa0, v14
	v_lshl_add_u64 v[18:19], s[10:11], 0, v[18:19]
	global_store_short v[24:25], v13, off
	v_cvt_pk_bf16_f32 v13, v15, v20
	v_add_lshl_u32 v14, v14, v44, 1
	v_mov_b32_e32 v15, v20
	v_lshl_add_u64 v[14:15], v[18:19], 0, v[14:15]
	global_store_short v[14:15], v13, off
	s_or_b64 exec, exec, s[44:45]
	s_and_saveexec_b64 s[42:43], s[40:41]
	s_cbranch_execnz .LBB0_262

.LBB0_269:
	v_bfe_u32 v14, v8, 7, 7
	v_bfe_u32 v15, v8, 14, 5
	v_ashrrev_i32_e32 v8, 19, v8
	v_mul_hi_i32_i24_e32 v11, 0x140000, v8
	v_mul_i32_i24_e32 v10, 0x140000, v8
	v_mad_u32_u24 v8, v15, s23, v14
	v_lshl_add_u64 v[12:13], s[8:9], 0, v[10:11]
	v_cvt_pk_bf16_f32 v17, v9, v20
	v_lshl_or_b32 v8, v8, 8, v27
	v_mov_b32_e32 v9, v20
	v_lshl_add_u64 v[8:9], v[12:13], 0, v[8:9]
	global_store_short v[8:9], v17, off
	v_lshl_or_b32 v8, v15, 7, v45
	v_mul_u32_u24_e32 v8, 0xa0, v8
	v_lshl_add_u64 v[10:11], s[10:11], 0, v[10:11]
	v_add_lshl_u32 v8, v8, v44, 1
	v_mov_b32_e32 v9, v20
	v_lshl_add_u64 v[8:9], v[10:11], 0, v[8:9]
	s_waitcnt vmcnt(4)
	v_cvt_pk_bf16_f32 v12, v29, v20
	global_store_short v[8:9], v12, off
	s_or_b64 exec, exec, s[40:41]
	s_and_saveexec_b64 s[38:39], vcc
	s_cbranch_execz .LBB0_256
.LBB0_270:
	v_bfe_u32 v14, v5, 7, 7
	v_bfe_u32 v15, v5, 14, 5
	v_ashrrev_i32_e32 v5, 19, v5
	v_mul_hi_i32_i24_e32 v9, 0x140000, v5
	v_mul_i32_i24_e32 v8, 0x140000, v5
	v_mad_u32_u24 v12, v15, s23, v14
	v_lshl_add_u64 v[10:11], s[8:9], 0, v[8:9]
	v_lshl_or_b32 v12, v12, 8, v27
	v_mov_b32_e32 v13, v20
	v_lshl_add_u64 v[10:11], v[10:11], 0, v[12:13]
	s_waitcnt vmcnt(2)
	v_cvt_pk_bf16_f32 v5, v23, v20
	global_store_short v[10:11], v5, off
	v_lshl_or_b32 v10, v15, 7, v45
	v_mul_u32_u24_e32 v10, 0xa0, v10
	v_lshl_add_u64 v[8:9], s[10:11], 0, v[8:9]
	v_add_lshl_u32 v10, v10, v44, 1
	v_mov_b32_e32 v11, v20
	v_lshl_add_u64 v[8:9], v[8:9], 0, v[10:11]
	v_cvt_pk_bf16_f32 v5, v16, v20
	global_store_short v[8:9], v5, off
	s_branch .LBB0_256

.LBB0_301:
	s_andn2_saveexec_b64 s[2:3], s[2:3]
	s_cbranch_execz .LBB0_310
	v_mad_u64_u32 v[0:1], s[4:5], s90, 6, v[0:1]
	s_movk_i32 s4, 0x4200
	s_nop 0
	v_cmp_gt_i32_e32 vcc, s4, v0
	s_and_saveexec_b64 s[4:5], vcc
	s_movk_i32 s14, 0x3fff
	s_cbranch_execz .LBB0_309
	v_and_b32_e32 v1, 64, v190
	s_waitcnt vmcnt(1)
	v_lshlrev_b32_e32 v8, 2, v4
	v_lshlrev_b32_e32 v2, 3, v4
	v_cmp_gt_u32_e32 vcc, 16, v4
	v_cmp_eq_u32_e64 s[38:39], 0, v4
	v_add_u32_e32 v1, 64, v1
	v_xor_b32_e32 v4, 1, v190
	v_cmp_lt_i32_e64 s[40:41], v4, v1
	s_load_dwordx4 s[44:47], s[0:1], 0x0
	s_mul_i32 s0, s74, 6
	v_cndmask_b32_e64 v4, v190, v4, s[40:41]
	s_waitcnt vmcnt(0)
	v_lshlrev_b32_e32 v14, 2, v4
	v_xor_b32_e32 v4, 2, v190
	v_cmp_lt_i32_e64 s[40:41], v4, v1
	v_mov_b32_e32 v9, v20
	v_mov_b32_e32 v3, v20
	v_cndmask_b32_e64 v4, v190, v4, s[40:41]
	v_lshlrev_b32_e32 v15, 2, v4
	v_xor_b32_e32 v4, 4, v190
	v_cmp_lt_i32_e64 s[40:41], v4, v1
	s_ashr_i32 s1, s0, 31
	v_lshl_add_u64 v[2:3], s[18:19], 0, v[2:3]
	v_cndmask_b32_e64 v4, v190, v4, s[40:41]
	v_lshlrev_b32_e32 v16, 2, v4
	v_xor_b32_e32 v4, 8, v190
	v_cmp_lt_i32_e64 s[40:41], v4, v1
	v_lshl_add_u64 v[6:7], s[78:79], 0, v[8:9]
	s_lshl_b64 s[6:7], s[0:1], 12
	v_cndmask_b32_e64 v4, v190, v4, s[40:41]
	v_lshlrev_b32_e32 v17, 2, v4
	v_xor_b32_e32 v4, 16, v190
	v_cmp_lt_i32_e64 s[40:41], v4, v1
	s_mov_b64 s[8:9], 0
	v_lshlrev_b32_e32 v8, 2, v8
	v_cndmask_b32_e64 v4, v190, v4, s[40:41]
	v_lshlrev_b32_e32 v18, 2, v4
	v_xor_b32_e32 v4, 32, v190
	v_cmp_lt_i32_e64 s[40:41], v4, v1
	s_nop 1
	v_cndmask_b32_e64 v1, v190, v4, s[40:41]
	v_lshlrev_b32_e32 v19, 2, v1
	v_ashrrev_i32_e32 v1, 31, v0
	v_lshlrev_b64 v[4:5], 12, v[0:1]
	s_waitcnt lgkmcnt(0)
	v_lshl_add_u64 v[4:5], s[44:45], 0, v[4:5]
	v_lshrrev_b32_e32 v48, 1, v8
	v_readfirstlane_b32 s8, v0
	s_nop 3
	s_cmp_gt_i32 s8, 0x3fff
	s_cselect_b32 s10, s46, s44
	s_cselect_b32 s11, s47, s45
	s_cselect_b32 s1, 0x4000, 0
	s_sub_i32 s1, s8, s1
	s_lshl_b32 s1, s1, 12
	s_add_u32 s10, s10, s1
	s_addc_u32 s11, s11, 0
	global_load_dwordx4 v[22:25], v8, s[10:11]
	global_load_dwordx4 v[26:29], v8, s[10:11] offset:1024
	global_load_dwordx4 v[30:33], v8, s[10:11] offset:2048
	global_load_dwordx4 v[34:37], v8, s[10:11] offset:3072
	s_add_i32 s9, s8, s0
	s_cmp_le_i32 s9, 0x41ff
	s_cselect_b32 s14, s9, s8
	s_cmp_gt_i32 s14, 0x3fff
	s_cselect_b32 s6, s46, s44
	s_cselect_b32 s7, s47, s45
	s_cselect_b32 s1, 0x4000, 0
	s_sub_i32 s1, s14, s1
	s_lshl_b32 s1, s1, 12
	s_add_u32 s6, s6, s1
	s_addc_u32 s7, s7, 0
	global_load_dwordx4 v[74:77], v8, s[6:7]
	global_load_dwordx4 v[78:81], v8, s[6:7] offset:1024
	global_load_dwordx4 v[82:85], v8, s[6:7] offset:2048
	global_load_dwordx4 v[86:89], v8, s[6:7] offset:3072
	s_lshl_b32 s1, s8, 11
	s_add_u32 s40, s18, s1
	s_addc_u32 s41, s19, 0
	s_waitcnt vmcnt(7)
	v_cvt_pk_bf16_f32 v40, v22, v23
	v_cvt_pk_bf16_f32 v41, v24, v25
	global_store_dwordx2 v48, v[40:41], s[40:41]
	v_mul_f32_e32 v9, v23, v23
	v_fmac_f32_e32 v9, v22, v22
	v_fmac_f32_e32 v9, v24, v24
	v_fmac_f32_e32 v9, v25, v25
	s_waitcnt vmcnt(7)
	v_cvt_pk_bf16_f32 v42, v26, v27
	v_cvt_pk_bf16_f32 v43, v28, v29
	global_store_dwordx2 v48, v[42:43], s[40:41] offset:512
	v_mul_f32_e32 v12, v27, v27
	v_fmac_f32_e32 v12, v26, v26
	v_fmac_f32_e32 v12, v28, v28
	v_fmac_f32_e32 v12, v29, v29
	v_add_f32_e32 v9, v9, v12
	s_waitcnt vmcnt(7)
	v_cvt_pk_bf16_f32 v44, v30, v31
	v_cvt_pk_bf16_f32 v45, v32, v33
	global_store_dwordx2 v48, v[44:45], s[40:41] offset:1024
	v_mul_f32_e32 v12, v31, v31
	v_fmac_f32_e32 v12, v30, v30
	v_fmac_f32_e32 v12, v32, v32
	v_fmac_f32_e32 v12, v33, v33
	v_add_f32_e32 v9, v9, v12
	s_waitcnt vmcnt(7)
	v_cvt_pk_bf16_f32 v46, v34, v35
	v_cvt_pk_bf16_f32 v47, v36, v37
	global_store_dwordx2 v48, v[46:47], s[40:41] offset:1536
	v_mul_f32_e32 v12, v35, v35
	v_fmac_f32_e32 v12, v34, v34
	v_fmac_f32_e32 v12, v36, v36
	v_fmac_f32_e32 v12, v37, v37
	v_add_f32_e32 v9, v9, v12
	ds_bpermute_b32 v12, v14, v9
	s_waitcnt lgkmcnt(0)
	v_add_f32_e32 v9, v9, v12
	ds_bpermute_b32 v12, v15, v9
	s_waitcnt lgkmcnt(0)
	v_add_f32_e32 v9, v9, v12
	ds_bpermute_b32 v12, v16, v9
	s_waitcnt lgkmcnt(0)
	v_add_f32_e32 v9, v9, v12
	ds_bpermute_b32 v12, v17, v9
	s_waitcnt lgkmcnt(0)
	v_add_f32_e32 v9, v9, v12
	ds_bpermute_b32 v12, v18, v9
	s_waitcnt lgkmcnt(0)
	v_add_f32_e32 v9, v9, v12
	ds_bpermute_b32 v12, v19, v9
	v_mov_b32_e32 v10, s8
	v_mov_b32_e32 v11, v20
	v_lshlrev_b64 v[10:11], 6, v[10:11]
	v_lshl_add_u64 v[10:11], v[6:7], 0, v[10:11]
	s_waitcnt lgkmcnt(0)
	v_add_f32_e32 v9, v9, v12
	v_cndmask_b32_e64 v9, 0, v9, s[38:39]
	s_mov_b64 exec, vcc
	global_store_dword v[10:11], v9, off
	s_mov_b64 exec, -1
	s_cmp_gt_i32 s9, 0x41ff
	s_cbranch_scc1 .Lt2_exit
	s_mov_b32 s8, s9
.Lt2_loop:
	s_add_i32 s9, s8, s0
	s_cmp_le_i32 s9, 0x41ff
	s_cselect_b32 s14, s9, s8
	s_cmp_gt_i32 s14, 0x3fff
	s_cselect_b32 s10, s46, s44
	s_cselect_b32 s11, s47, s45
	s_cselect_b32 s1, 0x4000, 0
	s_sub_i32 s1, s14, s1
	s_lshl_b32 s1, s1, 12
	s_add_u32 s10, s10, s1
	s_addc_u32 s11, s11, 0
	global_load_dwordx4 v[22:25], v8, s[10:11]
	global_load_dwordx4 v[26:29], v8, s[10:11] offset:1024
	global_load_dwordx4 v[30:33], v8, s[10:11] offset:2048
	global_load_dwordx4 v[34:37], v8, s[10:11] offset:3072
	s_lshl_b32 s1, s8, 11
	s_add_u32 s40, s18, s1
	s_addc_u32 s41, s19, 0
	s_waitcnt vmcnt(12)
	v_cvt_pk_bf16_f32 v40, v74, v75
	v_cvt_pk_bf16_f32 v41, v76, v77
	global_store_dwordx2 v48, v[40:41], s[40:41]
	v_mul_f32_e32 v9, v75, v75
	v_fmac_f32_e32 v9, v74, v74
	v_fmac_f32_e32 v9, v76, v76
	v_fmac_f32_e32 v9, v77, v77
	s_waitcnt vmcnt(12)
	v_cvt_pk_bf16_f32 v42, v78, v79
	v_cvt_pk_bf16_f32 v43, v80, v81
	global_store_dwordx2 v48, v[42:43], s[40:41] offset:512
	v_mul_f32_e32 v12, v79, v79
	v_fmac_f32_e32 v12, v78, v78
	v_fmac_f32_e32 v12, v80, v80
	v_fmac_f32_e32 v12, v81, v81
	v_add_f32_e32 v9, v9, v12
	s_waitcnt vmcnt(12)
	v_cvt_pk_bf16_f32 v44, v82, v83
	v_cvt_pk_bf16_f32 v45, v84, v85
	global_store_dwordx2 v48, v[44:45], s[40:41] offset:1024
	v_mul_f32_e32 v12, v83, v83
	v_fmac_f32_e32 v12, v82, v82
	v_fmac_f32_e32 v12, v84, v84
	v_fmac_f32_e32 v12, v85, v85
	v_add_f32_e32 v9, v9, v12
	s_waitcnt vmcnt(12)
	v_cvt_pk_bf16_f32 v46, v86, v87
	v_cvt_pk_bf16_f32 v47, v88, v89
	global_store_dwordx2 v48, v[46:47], s[40:41] offset:1536
	v_mul_f32_e32 v12, v87, v87
	v_fmac_f32_e32 v12, v86, v86
	v_fmac_f32_e32 v12, v88, v88
	v_fmac_f32_e32 v12, v89, v89
	v_add_f32_e32 v9, v9, v12
	ds_bpermute_b32 v12, v14, v9
	s_waitcnt lgkmcnt(0)
	v_add_f32_e32 v9, v9, v12
	ds_bpermute_b32 v12, v15, v9
	s_waitcnt lgkmcnt(0)
	v_add_f32_e32 v9, v9, v12
	ds_bpermute_b32 v12, v16, v9
	s_waitcnt lgkmcnt(0)
	v_add_f32_e32 v9, v9, v12
	ds_bpermute_b32 v12, v17, v9
	s_waitcnt lgkmcnt(0)
	v_add_f32_e32 v9, v9, v12
	ds_bpermute_b32 v12, v18, v9
	s_waitcnt lgkmcnt(0)
	v_add_f32_e32 v9, v9, v12
	ds_bpermute_b32 v12, v19, v9
	v_mov_b32_e32 v10, s8
	v_mov_b32_e32 v11, v20
	v_lshlrev_b64 v[10:11], 6, v[10:11]
	v_lshl_add_u64 v[10:11], v[6:7], 0, v[10:11]
	s_waitcnt lgkmcnt(0)
	v_add_f32_e32 v9, v9, v12
	v_cndmask_b32_e64 v9, 0, v9, s[38:39]
	s_mov_b64 exec, vcc
	global_store_dword v[10:11], v9, off
	s_mov_b64 exec, -1
	s_cmp_gt_i32 s9, 0x41ff
	s_cbranch_scc1 .Lt2_exit
	s_mov_b32 s8, s9
	s_add_i32 s9, s8, s0
	s_cmp_le_i32 s9, 0x41ff
	s_cselect_b32 s14, s9, s8
	s_cmp_gt_i32 s14, 0x3fff
	s_cselect_b32 s6, s46, s44
	s_cselect_b32 s7, s47, s45
	s_cselect_b32 s1, 0x4000, 0
	s_sub_i32 s1, s14, s1
	s_lshl_b32 s1, s1, 12
	s_add_u32 s6, s6, s1
	s_addc_u32 s7, s7, 0
	global_load_dwordx4 v[74:77], v8, s[6:7]
	global_load_dwordx4 v[78:81], v8, s[6:7] offset:1024
	global_load_dwordx4 v[82:85], v8, s[6:7] offset:2048
	global_load_dwordx4 v[86:89], v8, s[6:7] offset:3072
	s_lshl_b32 s1, s8, 11
	s_add_u32 s40, s18, s1
	s_addc_u32 s41, s19, 0
	s_waitcnt vmcnt(12)
	v_cvt_pk_bf16_f32 v40, v22, v23
	v_cvt_pk_bf16_f32 v41, v24, v25
	global_store_dwordx2 v48, v[40:41], s[40:41]
	v_mul_f32_e32 v9, v23, v23
	v_fmac_f32_e32 v9, v22, v22
	v_fmac_f32_e32 v9, v24, v24
	v_fmac_f32_e32 v9, v25, v25
	s_waitcnt vmcnt(12)
	v_cvt_pk_bf16_f32 v42, v26, v27
	v_cvt_pk_bf16_f32 v43, v28, v29
	global_store_dwordx2 v48, v[42:43], s[40:41] offset:512
	v_mul_f32_e32 v12, v27, v27
	v_fmac_f32_e32 v12, v26, v26
	v_fmac_f32_e32 v12, v28, v28
	v_fmac_f32_e32 v12, v29, v29
	v_add_f32_e32 v9, v9, v12
	s_waitcnt vmcnt(12)
	v_cvt_pk_bf16_f32 v44, v30, v31
	v_cvt_pk_bf16_f32 v45, v32, v33
	global_store_dwordx2 v48, v[44:45], s[40:41] offset:1024
	v_mul_f32_e32 v12, v31, v31
	v_fmac_f32_e32 v12, v30, v30
	v_fmac_f32_e32 v12, v32, v32
	v_fmac_f32_e32 v12, v33, v33
	v_add_f32_e32 v9, v9, v12
	s_waitcnt vmcnt(12)
	v_cvt_pk_bf16_f32 v46, v34, v35
	v_cvt_pk_bf16_f32 v47, v36, v37
	global_store_dwordx2 v48, v[46:47], s[40:41] offset:1536
	v_mul_f32_e32 v12, v35, v35
	v_fmac_f32_e32 v12, v34, v34
	v_fmac_f32_e32 v12, v36, v36
	v_fmac_f32_e32 v12, v37, v37
	v_add_f32_e32 v9, v9, v12
	ds_bpermute_b32 v12, v14, v9
	s_waitcnt lgkmcnt(0)
	v_add_f32_e32 v9, v9, v12
	ds_bpermute_b32 v12, v15, v9
	s_waitcnt lgkmcnt(0)
	v_add_f32_e32 v9, v9, v12
	ds_bpermute_b32 v12, v16, v9
	s_waitcnt lgkmcnt(0)
	v_add_f32_e32 v9, v9, v12
	ds_bpermute_b32 v12, v17, v9
	s_waitcnt lgkmcnt(0)
	v_add_f32_e32 v9, v9, v12
	ds_bpermute_b32 v12, v18, v9
	s_waitcnt lgkmcnt(0)
	v_add_f32_e32 v9, v9, v12
	ds_bpermute_b32 v12, v19, v9
	v_mov_b32_e32 v10, s8
	v_mov_b32_e32 v11, v20
	v_lshlrev_b64 v[10:11], 6, v[10:11]
	v_lshl_add_u64 v[10:11], v[6:7], 0, v[10:11]
	s_waitcnt lgkmcnt(0)
	v_add_f32_e32 v9, v9, v12
	v_cndmask_b32_e64 v9, 0, v9, s[38:39]
	s_mov_b64 exec, vcc
	global_store_dword v[10:11], v9, off
	s_mov_b64 exec, -1
	s_cmp_gt_i32 s9, 0x41ff
	s_cbranch_scc1 .Lt2_exit
	s_mov_b32 s8, s9
	s_branch .Lt2_loop
.Lt2_exit:
	s_waitcnt vmcnt(0)
.LBB0_309:
	s_or_b64 exec, exec, s[4:5]

.LBB0_320:
	global_load_dwordx2 v[14:15], v[10:11], off
	s_add_i32 s9, s8, 1
	s_cmp_lt_u32 s9, s11
	s_cselect_b64 s[38:39], -1, 0
	s_and_b64 s[16:17], s[38:39], exec
	v_pk_mul_f32 v[16:17], v[2:3], v[70:71]
	s_cselect_b32 s9, s9, s14
	v_pk_fma_f32 v[18:19], v[8:9], v[70:71], v[16:17] op_sel:[0,0,1] op_sel_hi:[1,1,0] neg_lo:[0,0,1] neg_hi:[0,0,1]
	v_pk_fma_f32 v[16:17], v[8:9], v[70:71], v[16:17] op_sel:[0,0,1] op_sel_hi:[1,1,0]
	s_add_i32 s27, s8, 2
	s_lshl_b32 s24, s9, 11
	v_mov_b32_e32 v19, v17
	v_lshl_add_u64 v[16:17], s[24:25], 2, v[4:5]
	s_cmp_lt_u32 s27, s11
	global_load_dwordx2 v[16:17], v[16:17], off
	s_cselect_b64 s[42:43], -1, 0
	s_and_b64 s[16:17], s[42:43], exec
	s_cselect_b32 s9, s27, s14
	s_add_i32 s27, s8, 3
	s_lshl_b32 s24, s9, 11
	s_cmp_lt_u32 s27, s11
	s_cselect_b64 s[44:45], -1, 0
	s_and_b64 s[16:17], s[44:45], exec
	s_cselect_b32 s9, s27, s14
	s_add_i32 s27, s8, 4
	v_lshl_add_u64 v[10:11], v[10:11], 0, s[20:21]
	s_waitcnt vmcnt(1)
	v_pk_add_f32 v[14:15], v[18:19], v[14:15]
	v_lshl_add_u64 v[18:19], s[24:25], 2, v[4:5]
	global_load_dwordx2 v[18:19], v[18:19], off
	s_lshl_b32 s24, s9, 11
	v_lshl_add_u64 v[22:23], s[24:25], 2, v[4:5]
	s_cmp_lt_u32 s27, s11
	global_load_dwordx2 v[22:23], v[22:23], off
	s_cselect_b64 vcc, -1, 0
	s_and_b64 s[16:17], vcc, exec
	s_cselect_b32 s9, s27, s14
	s_lshl_b32 s24, s9, 11
	v_lshl_add_u64 v[24:25], s[24:25], 2, v[4:5]
	global_load_dwordx2 v[24:25], v[24:25], off
	v_pk_mul_f32 v[26:27], v[2:3], v[14:15]
	s_add_i32 s9, s8, 5
	v_pk_fma_f32 v[28:29], v[8:9], v[14:15], v[26:27] op_sel:[0,0,1] op_sel_hi:[1,1,0] neg_lo:[0,0,1] neg_hi:[0,0,1]
	v_pk_fma_f32 v[26:27], v[8:9], v[14:15], v[26:27] op_sel:[0,0,1] op_sel_hi:[1,1,0]
	s_cmp_lt_u32 s9, s11
	v_mov_b32_e32 v29, v27
	s_waitcnt vmcnt(3)
	v_pk_add_f32 v[16:17], v[16:17], v[28:29]
	s_nop 0
	v_cndmask_b32_e64 v15, v15, v17, s[38:39]
	v_cndmask_b32_e64 v14, v14, v16, s[38:39]
	v_pk_mul_f32 v[16:17], v[2:3], v[14:15]
	s_cselect_b64 s[38:39], -1, 0
	v_pk_fma_f32 v[26:27], v[8:9], v[14:15], v[16:17] op_sel:[0,0,1] op_sel_hi:[1,1,0] neg_lo:[0,0,1] neg_hi:[0,0,1]
	v_pk_fma_f32 v[16:17], v[8:9], v[14:15], v[16:17] op_sel:[0,0,1] op_sel_hi:[1,1,0]
	s_and_b64 s[16:17], s[38:39], exec
	v_mov_b32_e32 v27, v17
	s_cselect_b32 s9, s9, s14
	s_add_i32 s27, s8, 6
	s_lshl_b32 s24, s9, 11
	s_cmp_lt_u32 s27, s11
	s_waitcnt vmcnt(2)
	v_pk_add_f32 v[16:17], v[18:19], v[26:27]
	s_nop 0
	v_cndmask_b32_e64 v15, v15, v17, s[42:43]
	v_cndmask_b32_e64 v14, v14, v16, s[42:43]
	v_pk_mul_f32 v[16:17], v[2:3], v[14:15]
	s_cselect_b64 s[42:43], -1, 0
	v_pk_fma_f32 v[18:19], v[8:9], v[14:15], v[16:17] op_sel:[0,0,1] op_sel_hi:[1,1,0] neg_lo:[0,0,1] neg_hi:[0,0,1]
	v_pk_fma_f32 v[16:17], v[8:9], v[14:15], v[16:17] op_sel:[0,0,1] op_sel_hi:[1,1,0]
	s_and_b64 s[16:17], s[42:43], exec
	v_mov_b32_e32 v19, v17
	s_waitcnt vmcnt(1)
	v_pk_add_f32 v[16:17], v[22:23], v[18:19]
	s_cselect_b32 s9, s27, s14
	v_cndmask_b32_e64 v15, v15, v17, s[44:45]
	v_cndmask_b32_e64 v14, v14, v16, s[44:45]
	v_pk_mul_f32 v[16:17], v[2:3], v[14:15]
	s_add_i32 s27, s8, 7
	v_pk_fma_f32 v[18:19], v[8:9], v[14:15], v[16:17] op_sel:[0,0,1] op_sel_hi:[1,1,0] neg_lo:[0,0,1] neg_hi:[0,0,1]
	v_pk_fma_f32 v[16:17], v[8:9], v[14:15], v[16:17] op_sel:[0,0,1] op_sel_hi:[1,1,0]
	s_nop 0
	v_mov_b32_e32 v19, v17
	s_waitcnt vmcnt(0)
	v_pk_add_f32 v[16:17], v[24:25], v[18:19]
	v_lshl_add_u64 v[18:19], s[24:25], 2, v[4:5]
	global_load_dwordx2 v[18:19], v[18:19], off
	s_lshl_b32 s24, s9, 11
	v_lshl_add_u64 v[22:23], s[24:25], 2, v[4:5]
	s_cmp_lt_u32 s27, s11
	global_load_dwordx2 v[22:23], v[22:23], off
	s_cselect_b64 s[44:45], -1, 0
	s_and_b64 s[16:17], s[44:45], exec
	s_cselect_b32 s9, s27, s14
	s_lshl_b32 s24, s9, 11
	v_lshl_add_u64 v[24:25], s[24:25], 2, v[4:5]
	global_load_dwordx2 v[24:25], v[24:25], off
	v_cndmask_b32_e32 v15, v15, v17, vcc
	v_cndmask_b32_e32 v14, v14, v16, vcc
	v_pk_mul_f32 v[16:17], v[2:3], v[14:15]
	s_add_i32 s8, s8, 8
	v_pk_fma_f32 v[26:27], v[8:9], v[14:15], v[16:17] op_sel:[0,0,1] op_sel_hi:[1,1,0] neg_lo:[0,0,1] neg_hi:[0,0,1]
	v_pk_fma_f32 v[16:17], v[8:9], v[14:15], v[16:17] op_sel:[0,0,1] op_sel_hi:[1,1,0]
	s_cmp_lt_u32 s8, s11
	v_mov_b32_e32 v27, v17
	s_waitcnt vmcnt(2)
	v_pk_add_f32 v[16:17], v[18:19], v[26:27]
	s_nop 0
	v_cndmask_b32_e64 v15, v15, v17, s[38:39]
	v_cndmask_b32_e64 v14, v14, v16, s[38:39]
	v_pk_mul_f32 v[16:17], v[2:3], v[14:15]
	s_nop 0
	v_pk_fma_f32 v[18:19], v[8:9], v[14:15], v[16:17] op_sel:[0,0,1] op_sel_hi:[1,1,0] neg_lo:[0,0,1] neg_hi:[0,0,1]
	v_pk_fma_f32 v[16:17], v[8:9], v[14:15], v[16:17] op_sel:[0,0,1] op_sel_hi:[1,1,0]
	s_nop 0
	v_mov_b32_e32 v19, v17
	s_waitcnt vmcnt(1)
	v_pk_add_f32 v[16:17], v[22:23], v[18:19]
	s_nop 0
	v_cndmask_b32_e64 v15, v15, v17, s[42:43]
	v_cndmask_b32_e64 v14, v14, v16, s[42:43]
	v_pk_mul_f32 v[16:17], v[2:3], v[14:15]
	s_nop 0
	v_pk_fma_f32 v[18:19], v[8:9], v[14:15], v[16:17] op_sel:[0,0,1] op_sel_hi:[1,1,0] neg_lo:[0,0,1] neg_hi:[0,0,1]
	v_pk_fma_f32 v[16:17], v[8:9], v[14:15], v[16:17] op_sel:[0,0,1] op_sel_hi:[1,1,0]
	s_nop 0
	v_mov_b32_e32 v19, v17
	s_waitcnt vmcnt(0)
	v_pk_add_f32 v[16:17], v[24:25], v[18:19]
	s_nop 0
	v_cndmask_b32_e64 v70, v14, v16, s[44:45]
	v_cndmask_b32_e64 v71, v15, v17, s[44:45]
	s_cbranch_scc1 .LBB0_320
	s_branch .LBB0_328

.LBB0_334:
	global_load_dwordx2 v[14:15], v[10:11], off
	s_add_i32 s9, s8, 1
	s_cmp_lt_u32 s9, s11
	s_cselect_b64 s[42:43], -1, 0
	s_and_b64 s[16:17], s[42:43], exec
	v_pk_mul_f32 v[16:17], v[4:5], v[72:73]
	s_cselect_b32 s9, s9, s14
	v_pk_fma_f32 v[18:19], v[8:9], v[72:73], v[16:17] op_sel:[0,0,1] op_sel_hi:[1,1,0] neg_lo:[0,0,1] neg_hi:[0,0,1]
	v_pk_fma_f32 v[16:17], v[8:9], v[72:73], v[16:17] op_sel:[0,0,1] op_sel_hi:[1,1,0]
	s_add_i32 s29, s8, 2
	s_lshl_b32 s24, s9, 11
	v_mov_b32_e32 v19, v17
	v_lshl_add_u64 v[16:17], s[24:25], 2, v[6:7]
	s_cmp_lt_u32 s29, s11
	global_load_dwordx2 v[16:17], v[16:17], off
	s_cselect_b64 s[44:45], -1, 0
	s_and_b64 s[16:17], s[44:45], exec
	s_cselect_b32 s9, s29, s14
	s_add_i32 s29, s8, 3
	s_lshl_b32 s24, s9, 11
	s_cmp_lt_u32 s29, s11
	s_cselect_b64 s[46:47], -1, 0
	s_and_b64 s[16:17], s[46:47], exec
	s_cselect_b32 s9, s29, s14
	s_add_i32 s29, s8, 4
	v_lshl_add_u64 v[10:11], v[10:11], 0, s[20:21]
	s_waitcnt vmcnt(1)
	v_pk_add_f32 v[14:15], v[18:19], v[14:15]
	v_lshl_add_u64 v[18:19], s[24:25], 2, v[6:7]
	global_load_dwordx2 v[18:19], v[18:19], off
	s_lshl_b32 s24, s9, 11
	v_lshl_add_u64 v[22:23], s[24:25], 2, v[6:7]
	s_cmp_lt_u32 s29, s11
	global_load_dwordx2 v[22:23], v[22:23], off
	s_cselect_b64 vcc, -1, 0
	s_and_b64 s[16:17], vcc, exec
	s_cselect_b32 s9, s29, s14
	s_lshl_b32 s24, s9, 11
	v_lshl_add_u64 v[24:25], s[24:25], 2, v[6:7]
	global_load_dwordx2 v[24:25], v[24:25], off
	v_pk_mul_f32 v[26:27], v[4:5], v[14:15]
	s_add_i32 s9, s8, 5
	v_pk_fma_f32 v[28:29], v[8:9], v[14:15], v[26:27] op_sel:[0,0,1] op_sel_hi:[1,1,0] neg_lo:[0,0,1] neg_hi:[0,0,1]
	v_pk_fma_f32 v[26:27], v[8:9], v[14:15], v[26:27] op_sel:[0,0,1] op_sel_hi:[1,1,0]
	s_cmp_lt_u32 s9, s11
	v_mov_b32_e32 v29, v27
	s_waitcnt vmcnt(3)
	v_pk_add_f32 v[16:17], v[16:17], v[28:29]
	s_nop 0
	v_cndmask_b32_e64 v15, v15, v17, s[42:43]
	v_cndmask_b32_e64 v14, v14, v16, s[42:43]
	v_pk_mul_f32 v[16:17], v[4:5], v[14:15]
	s_cselect_b64 s[42:43], -1, 0
	v_pk_fma_f32 v[26:27], v[8:9], v[14:15], v[16:17] op_sel:[0,0,1] op_sel_hi:[1,1,0] neg_lo:[0,0,1] neg_hi:[0,0,1]
	v_pk_fma_f32 v[16:17], v[8:9], v[14:15], v[16:17] op_sel:[0,0,1] op_sel_hi:[1,1,0]
	s_and_b64 s[16:17], s[42:43], exec
	v_mov_b32_e32 v27, v17
	s_cselect_b32 s9, s9, s14
	s_add_i32 s29, s8, 6
	s_lshl_b32 s24, s9, 11
	s_cmp_lt_u32 s29, s11
	s_waitcnt vmcnt(2)
	v_pk_add_f32 v[16:17], v[18:19], v[26:27]
	s_nop 0
	v_cndmask_b32_e64 v15, v15, v17, s[44:45]
	v_cndmask_b32_e64 v14, v14, v16, s[44:45]
	v_pk_mul_f32 v[16:17], v[4:5], v[14:15]
	s_cselect_b64 s[44:45], -1, 0
	v_pk_fma_f32 v[18:19], v[8:9], v[14:15], v[16:17] op_sel:[0,0,1] op_sel_hi:[1,1,0] neg_lo:[0,0,1] neg_hi:[0,0,1]
	v_pk_fma_f32 v[16:17], v[8:9], v[14:15], v[16:17] op_sel:[0,0,1] op_sel_hi:[1,1,0]
	s_and_b64 s[16:17], s[44:45], exec
	v_mov_b32_e32 v19, v17
	s_waitcnt vmcnt(1)
	v_pk_add_f32 v[16:17], v[22:23], v[18:19]
	s_cselect_b32 s9, s29, s14
	v_cndmask_b32_e64 v15, v15, v17, s[46:47]
	v_cndmask_b32_e64 v14, v14, v16, s[46:47]
	v_pk_mul_f32 v[16:17], v[4:5], v[14:15]
	s_add_i32 s29, s8, 7
	v_pk_fma_f32 v[18:19], v[8:9], v[14:15], v[16:17] op_sel:[0,0,1] op_sel_hi:[1,1,0] neg_lo:[0,0,1] neg_hi:[0,0,1]
	v_pk_fma_f32 v[16:17], v[8:9], v[14:15], v[16:17] op_sel:[0,0,1] op_sel_hi:[1,1,0]
	s_nop 0
	v_mov_b32_e32 v19, v17
	s_waitcnt vmcnt(0)
	v_pk_add_f32 v[16:17], v[24:25], v[18:19]
	v_lshl_add_u64 v[18:19], s[24:25], 2, v[6:7]
	global_load_dwordx2 v[18:19], v[18:19], off
	s_lshl_b32 s24, s9, 11
	v_lshl_add_u64 v[22:23], s[24:25], 2, v[6:7]
	s_cmp_lt_u32 s29, s11
	global_load_dwordx2 v[22:23], v[22:23], off
	s_cselect_b64 s[46:47], -1, 0
	s_and_b64 s[16:17], s[46:47], exec
	s_cselect_b32 s9, s29, s14
	s_lshl_b32 s24, s9, 11
	v_lshl_add_u64 v[24:25], s[24:25], 2, v[6:7]
	global_load_dwordx2 v[24:25], v[24:25], off
	v_cndmask_b32_e32 v15, v15, v17, vcc
	v_cndmask_b32_e32 v14, v14, v16, vcc
	v_pk_mul_f32 v[16:17], v[4:5], v[14:15]
	s_add_i32 s8, s8, 8
	v_pk_fma_f32 v[26:27], v[8:9], v[14:15], v[16:17] op_sel:[0,0,1] op_sel_hi:[1,1,0] neg_lo:[0,0,1] neg_hi:[0,0,1]
	v_pk_fma_f32 v[16:17], v[8:9], v[14:15], v[16:17] op_sel:[0,0,1] op_sel_hi:[1,1,0]
	s_cmp_ge_u32 s8, s11
	v_mov_b32_e32 v27, v17
	s_waitcnt vmcnt(2)
	v_pk_add_f32 v[16:17], v[18:19], v[26:27]
	s_nop 0
	v_cndmask_b32_e64 v15, v15, v17, s[42:43]
	v_cndmask_b32_e64 v14, v14, v16, s[42:43]
	v_pk_mul_f32 v[16:17], v[4:5], v[14:15]
	s_nop 0
	v_pk_fma_f32 v[18:19], v[8:9], v[14:15], v[16:17] op_sel:[0,0,1] op_sel_hi:[1,1,0] neg_lo:[0,0,1] neg_hi:[0,0,1]
	v_pk_fma_f32 v[16:17], v[8:9], v[14:15], v[16:17] op_sel:[0,0,1] op_sel_hi:[1,1,0]
	s_nop 0
	v_mov_b32_e32 v19, v17
	s_waitcnt vmcnt(1)
	v_pk_add_f32 v[16:17], v[22:23], v[18:19]
	s_nop 0
	v_cndmask_b32_e64 v15, v15, v17, s[44:45]
	v_cndmask_b32_e64 v14, v14, v16, s[44:45]
	v_pk_mul_f32 v[16:17], v[4:5], v[14:15]
	s_nop 0
	v_pk_fma_f32 v[18:19], v[8:9], v[14:15], v[16:17] op_sel:[0,0,1] op_sel_hi:[1,1,0] neg_lo:[0,0,1] neg_hi:[0,0,1]
	v_pk_fma_f32 v[16:17], v[8:9], v[14:15], v[16:17] op_sel:[0,0,1] op_sel_hi:[1,1,0]
	s_nop 0
	v_mov_b32_e32 v19, v17
	s_waitcnt vmcnt(0)
	v_pk_add_f32 v[16:17], v[24:25], v[18:19]
	s_nop 0
	v_cndmask_b32_e64 v72, v14, v16, s[46:47]
	v_cndmask_b32_e64 v73, v15, v17, s[46:47]
	s_cbranch_scc0 .LBB0_334
	s_cbranch_execz .LBB0_341

.LBB0_339:
	global_load_dwordx4 v[14:17], v[10:11], off offset:1024
	global_load_dwordx4 v[22:25], v[10:11], off
	s_add_i32 s14, s7, 1
	s_cmp_lt_u32 s14, s11
	s_cselect_b64 vcc, -1, 0
	s_and_b64 s[8:9], vcc, exec
	s_cselect_b32 s8, s14, s6
	s_lshl_b32 s24, s8, 9
	s_add_i32 s14, s7, 2
	s_cmp_lt_u32 s14, s11
	s_cselect_b64 s[40:41], -1, 0
	s_and_b64 s[8:9], s[40:41], exec
	s_cselect_b32 s8, s14, s6
	s_add_i32 s14, s7, 3
	v_lshl_add_u64 v[10:11], v[10:11], 0, s[52:53]
	s_waitcnt vmcnt(0)
	v_pk_fma_f32 v[6:7], v[6:7], v[24:25], v[16:17]
	v_lshl_add_u64 v[24:25], s[24:25], 2, v[8:9]
	global_load_dwordx4 v[16:19], v[24:25], off
	s_nop 0
	global_load_dwordx4 v[24:27], v[24:25], off offset:1024
	s_lshl_b32 s24, s8, 9
	v_lshl_add_u64 v[30:31], s[24:25], 2, v[8:9]
	s_cmp_lt_u32 s14, s11
	s_cselect_b64 s[42:43], -1, 0
	s_and_b64 s[8:9], s[42:43], exec
	s_cselect_b32 s8, s14, s6
	s_lshl_b32 s24, s8, 9
	v_pk_fma_f32 v[4:5], v[4:5], v[22:23], v[14:15]
	s_add_i32 s7, s7, 4
	s_cmp_lt_u32 s7, s11
	s_waitcnt vmcnt(0)
	v_pk_fma_f32 v[18:19], v[18:19], v[6:7], v[26:27]
	global_load_dwordx4 v[26:29], v[30:31], off
	s_nop 0
	global_load_dwordx4 v[30:33], v[30:31], off offset:1024
	v_cndmask_b32_e32 v7, v7, v19, vcc
	v_cndmask_b32_e32 v6, v6, v18, vcc
	v_pk_fma_f32 v[14:15], v[16:17], v[4:5], v[24:25]
	s_waitcnt vmcnt(0)
	v_pk_fma_f32 v[18:19], v[28:29], v[6:7], v[32:33]
	s_nop 0
	v_cndmask_b32_e64 v7, v7, v19, s[40:41]
	v_cndmask_b32_e64 v6, v6, v18, s[40:41]
	v_lshl_add_u64 v[18:19], s[24:25], 2, v[8:9]
	global_load_dwordx4 v[32:35], v[18:19], off
	global_load_dwordx4 v[36:39], v[18:19], off offset:1024
	v_cndmask_b32_e32 v5, v5, v15, vcc
	v_cndmask_b32_e32 v4, v4, v14, vcc
	v_pk_fma_f32 v[14:15], v[26:27], v[4:5], v[30:31]
	s_nop 0
	v_cndmask_b32_e64 v5, v5, v15, s[40:41]
	v_cndmask_b32_e64 v4, v4, v14, s[40:41]
	s_waitcnt vmcnt(0)
	v_pk_fma_f32 v[14:15], v[34:35], v[6:7], v[38:39]
	v_pk_fma_f32 v[16:17], v[32:33], v[4:5], v[36:37]
	v_cndmask_b32_e64 v6, v6, v14, s[42:43]
	v_cndmask_b32_e64 v7, v7, v15, s[42:43]
	v_cndmask_b32_e64 v4, v4, v16, s[42:43]
	v_cndmask_b32_e64 v5, v5, v17, s[42:43]
	s_cbranch_scc1 .LBB0_339
	s_branch .LBB0_451

.LBB0_2090:
	s_and_b32 s4, s8, 0xffffffe0
	s_and_b32 s11, s10, 15
	v_or_b32_e32 v5, s4, v21
	v_mad_i64_i32 v[6:7], s[12:13], v5, s91, v[0:1]
	v_lshl_or_b32 v5, s11, 6, v21
	v_mul_u32_u24_e32 v5, 0xb00, v5
	v_lshlrev_b32_e32 v16, 1, v5
	v_mov_b32_e32 v17, v20
	v_add_co_u32_e32 v148, vcc, 0x16000, v6
	v_lshl_add_u64 v[146:147], v[2:3], 0, v[16:17]
	s_nop 0
	v_addc_co_u32_e32 v149, vcc, 0, v7, vcc
	v_add_co_u32_e32 v156, vcc, 0x16000, v146
	s_nop 1
	v_addc_co_u32_e32 v157, vcc, 0, v147, vcc
	v_add_co_u32_e32 v162, vcc, 0x2c000, v146
	s_nop 1
	v_addc_co_u32_e32 v163, vcc, 0, v147, vcc
	v_add_co_u32_e32 v164, vcc, 0x42000, v146
	s_nop 1
	v_addc_co_u32_e32 v165, vcc, 0, v147, vcc
	global_load_dwordx4 v[16:19], v[6:7], off
	global_load_dwordx4 v[22:25], v[6:7], off offset:64
	global_load_dwordx4 v[26:29], v[148:149], off
	global_load_dwordx4 v[30:33], v[148:149], off offset:64
	global_load_dwordx4 v[34:37], v[146:147], off
	global_load_dwordx4 v[38:41], v[146:147], off offset:64
	global_load_dwordx4 v[42:45], v[156:157], off
	global_load_dwordx4 v[46:49], v[156:157], off offset:64
	global_load_dwordx4 v[50:53], v[162:163], off
	global_load_dwordx4 v[54:57], v[162:163], off offset:64
	global_load_dwordx4 v[58:61], v[164:165], off
	global_load_dwordx4 v[62:65], v[164:165], off offset:64
	global_load_dwordx4 v[66:69], v[6:7], off offset:128
	global_load_dwordx4 v[70:73], v[6:7], off offset:192
	global_load_dwordx4 v[74:77], v[148:149], off offset:128
	global_load_dwordx4 v[78:81], v[148:149], off offset:192
	global_load_dwordx4 v[82:85], v[146:147], off offset:128
	global_load_dwordx4 v[86:89], v[146:147], off offset:192
	global_load_dwordx4 v[90:93], v[156:157], off offset:128
	global_load_dwordx4 v[94:97], v[156:157], off offset:192
	global_load_dwordx4 v[98:101], v[162:163], off offset:128
	global_load_dwordx4 v[102:105], v[162:163], off offset:192
	global_load_dwordx4 v[106:109], v[164:165], off offset:128
	global_load_dwordx4 v[110:113], v[164:165], off offset:192
	s_waitcnt vmcnt(19)
	v_mfma_f32_16x16x32_bf16 v[114:117], v[34:37], v[16:19], 0
	s_waitcnt vmcnt(17)
	v_mfma_f32_16x16x32_bf16 v[118:121], v[42:45], v[16:19], 0
	s_waitcnt vmcnt(15)
	v_mfma_f32_16x16x32_bf16 v[122:125], v[50:53], v[16:19], 0
	s_waitcnt vmcnt(13)
	v_mfma_f32_16x16x32_bf16 v[16:19], v[58:61], v[16:19], 0
	v_mfma_f32_16x16x32_bf16 v[34:37], v[34:37], v[26:29], 0
	v_mfma_f32_16x16x32_bf16 v[42:45], v[42:45], v[26:29], 0
	v_mfma_f32_16x16x32_bf16 v[50:53], v[50:53], v[26:29], 0
	v_mfma_f32_16x16x32_bf16 v[26:29], v[58:61], v[26:29], 0
	v_mfma_f32_16x16x32_bf16 v[58:61], v[38:41], v[22:25], v[114:117]
	v_mfma_f32_16x16x32_bf16 v[114:117], v[46:49], v[22:25], v[118:121]
	v_mfma_f32_16x16x32_bf16 v[118:121], v[54:57], v[22:25], v[122:125]
	s_waitcnt vmcnt(12)
	v_mfma_f32_16x16x32_bf16 v[16:19], v[62:65], v[22:25], v[16:19]
	v_mfma_f32_16x16x32_bf16 v[22:25], v[38:41], v[30:33], v[34:37]
	v_mfma_f32_16x16x32_bf16 v[34:37], v[46:49], v[30:33], v[42:45]
	v_mfma_f32_16x16x32_bf16 v[38:41], v[54:57], v[30:33], v[50:53]
	v_mfma_f32_16x16x32_bf16 v[26:29], v[62:65], v[30:33], v[26:29]
	s_waitcnt vmcnt(7)
	v_mfma_f32_16x16x32_bf16 v[30:33], v[82:85], v[66:69], v[58:61]
	s_waitcnt vmcnt(5)
	v_mfma_f32_16x16x32_bf16 v[42:45], v[90:93], v[66:69], v[114:117]
	s_waitcnt vmcnt(3)
	v_mfma_f32_16x16x32_bf16 v[46:49], v[98:101], v[66:69], v[118:121]
	s_waitcnt vmcnt(1)
	v_mfma_f32_16x16x32_bf16 v[16:19], v[106:109], v[66:69], v[16:19]
	v_mfma_f32_16x16x32_bf16 v[22:25], v[82:85], v[74:77], v[22:25]
	v_mfma_f32_16x16x32_bf16 v[34:37], v[90:93], v[74:77], v[34:37]
	v_mfma_f32_16x16x32_bf16 v[38:41], v[98:101], v[74:77], v[38:41]
	v_mfma_f32_16x16x32_bf16 v[26:29], v[106:109], v[74:77], v[26:29]
	v_mfma_f32_16x16x32_bf16 v[30:33], v[86:89], v[70:73], v[30:33]
	v_mfma_f32_16x16x32_bf16 v[42:45], v[94:97], v[70:73], v[42:45]
	v_mfma_f32_16x16x32_bf16 v[46:49], v[102:105], v[70:73], v[46:49]
	s_waitcnt vmcnt(0)
	v_mfma_f32_16x16x32_bf16 v[16:19], v[110:113], v[70:73], v[16:19]
	v_mfma_f32_16x16x32_bf16 v[22:25], v[86:89], v[78:81], v[22:25]
	v_mfma_f32_16x16x32_bf16 v[34:37], v[94:97], v[78:81], v[34:37]
	v_mfma_f32_16x16x32_bf16 v[38:41], v[102:105], v[78:81], v[38:41]
	v_mfma_f32_16x16x32_bf16 v[26:29], v[110:113], v[78:81], v[26:29]
	global_load_dwordx4 v[50:53], v[6:7], off offset:256
	global_load_dwordx4 v[54:57], v[6:7], off offset:320
	global_load_dwordx4 v[58:61], v[148:149], off offset:256
	global_load_dwordx4 v[62:65], v[148:149], off offset:320
	global_load_dwordx4 v[66:69], v[146:147], off offset:256
	global_load_dwordx4 v[70:73], v[146:147], off offset:320
	global_load_dwordx4 v[74:77], v[156:157], off offset:256
	global_load_dwordx4 v[78:81], v[156:157], off offset:320
	global_load_dwordx4 v[82:85], v[162:163], off offset:256
	global_load_dwordx4 v[86:89], v[162:163], off offset:320
	global_load_dwordx4 v[90:93], v[164:165], off offset:256
	global_load_dwordx4 v[94:97], v[164:165], off offset:320
	global_load_dwordx4 v[98:101], v[6:7], off offset:384
	global_load_dwordx4 v[102:105], v[6:7], off offset:448
	global_load_dwordx4 v[106:109], v[148:149], off offset:384
	global_load_dwordx4 v[110:113], v[148:149], off offset:448
	global_load_dwordx4 v[114:117], v[146:147], off offset:384
	global_load_dwordx4 v[118:121], v[146:147], off offset:448
	global_load_dwordx4 v[122:125], v[156:157], off offset:384
	global_load_dwordx4 v[126:129], v[156:157], off offset:448
	global_load_dwordx4 v[130:133], v[162:163], off offset:384
	global_load_dwordx4 v[134:137], v[162:163], off offset:448
	global_load_dwordx4 v[138:141], v[164:165], off offset:384
	global_load_dwordx4 v[142:145], v[164:165], off offset:448
	s_waitcnt vmcnt(19)
	v_mfma_f32_16x16x32_bf16 v[30:33], v[66:69], v[50:53], v[30:33]
	s_waitcnt vmcnt(17)
	v_mfma_f32_16x16x32_bf16 v[42:45], v[74:77], v[50:53], v[42:45]
	s_waitcnt vmcnt(15)
	v_mfma_f32_16x16x32_bf16 v[46:49], v[82:85], v[50:53], v[46:49]
	s_waitcnt vmcnt(13)
	v_mfma_f32_16x16x32_bf16 v[16:19], v[90:93], v[50:53], v[16:19]
	v_mfma_f32_16x16x32_bf16 v[22:25], v[66:69], v[58:61], v[22:25]
	v_mfma_f32_16x16x32_bf16 v[34:37], v[74:77], v[58:61], v[34:37]
	v_mfma_f32_16x16x32_bf16 v[38:41], v[82:85], v[58:61], v[38:41]
	v_mfma_f32_16x16x32_bf16 v[26:29], v[90:93], v[58:61], v[26:29]
	v_mfma_f32_16x16x32_bf16 v[30:33], v[70:73], v[54:57], v[30:33]
	v_mfma_f32_16x16x32_bf16 v[42:45], v[78:81], v[54:57], v[42:45]
	v_mfma_f32_16x16x32_bf16 v[46:49], v[86:89], v[54:57], v[46:49]
	s_waitcnt vmcnt(12)
	v_mfma_f32_16x16x32_bf16 v[16:19], v[94:97], v[54:57], v[16:19]
	v_mfma_f32_16x16x32_bf16 v[22:25], v[70:73], v[62:65], v[22:25]
	v_mfma_f32_16x16x32_bf16 v[34:37], v[78:81], v[62:65], v[34:37]
	v_mfma_f32_16x16x32_bf16 v[38:41], v[86:89], v[62:65], v[38:41]
	v_mfma_f32_16x16x32_bf16 v[26:29], v[94:97], v[62:65], v[26:29]
	s_waitcnt vmcnt(7)
	v_mfma_f32_16x16x32_bf16 v[30:33], v[114:117], v[98:101], v[30:33]
	s_waitcnt vmcnt(5)
	v_mfma_f32_16x16x32_bf16 v[42:45], v[122:125], v[98:101], v[42:45]
	s_waitcnt vmcnt(3)
	v_mfma_f32_16x16x32_bf16 v[46:49], v[130:133], v[98:101], v[46:49]
	s_waitcnt vmcnt(1)
	v_mfma_f32_16x16x32_bf16 v[16:19], v[138:141], v[98:101], v[16:19]
	v_mfma_f32_16x16x32_bf16 v[22:25], v[114:117], v[106:109], v[22:25]
	v_mfma_f32_16x16x32_bf16 v[34:37], v[122:125], v[106:109], v[34:37]
	v_mfma_f32_16x16x32_bf16 v[38:41], v[130:133], v[106:109], v[38:41]
	v_mfma_f32_16x16x32_bf16 v[26:29], v[138:141], v[106:109], v[26:29]
	v_mfma_f32_16x16x32_bf16 v[30:33], v[118:121], v[102:105], v[30:33]
	v_mfma_f32_16x16x32_bf16 v[42:45], v[126:129], v[102:105], v[42:45]
	v_mfma_f32_16x16x32_bf16 v[46:49], v[134:137], v[102:105], v[46:49]
	s_waitcnt vmcnt(0)
	v_mfma_f32_16x16x32_bf16 v[16:19], v[142:145], v[102:105], v[16:19]
	v_mfma_f32_16x16x32_bf16 v[22:25], v[118:121], v[110:113], v[22:25]
	v_mfma_f32_16x16x32_bf16 v[34:37], v[126:129], v[110:113], v[34:37]
	v_mfma_f32_16x16x32_bf16 v[38:41], v[134:137], v[110:113], v[38:41]
	v_mfma_f32_16x16x32_bf16 v[26:29], v[142:145], v[110:113], v[26:29]
	global_load_dwordx4 v[50:53], v[6:7], off offset:512
	global_load_dwordx4 v[54:57], v[6:7], off offset:576
	global_load_dwordx4 v[58:61], v[148:149], off offset:512
	global_load_dwordx4 v[62:65], v[148:149], off offset:576
	global_load_dwordx4 v[66:69], v[162:163], off offset:512
	global_load_dwordx4 v[70:73], v[162:163], off offset:576
	global_load_dwordx4 v[74:77], v[146:147], off offset:512
	global_load_dwordx4 v[78:81], v[6:7], off offset:640
	global_load_dwordx4 v[82:85], v[156:157], off offset:512
	global_load_dwordx4 v[86:89], v[148:149], off offset:640
	global_load_dwordx4 v[90:93], v[146:147], off offset:576
	global_load_dwordx4 v[94:97], v[146:147], off offset:640
	global_load_dwordx4 v[98:101], v[156:157], off offset:576
	global_load_dwordx4 v[102:105], v[156:157], off offset:640
	global_load_dwordx4 v[106:109], v[164:165], off offset:512
	global_load_dwordx4 v[110:113], v[162:163], off offset:640
	global_load_dwordx4 v[114:117], v[164:165], off offset:576
	global_load_dwordx4 v[118:121], v[164:165], off offset:640
	s_waitcnt vmcnt(11)
	v_mfma_f32_16x16x32_bf16 v[30:33], v[74:77], v[50:53], v[30:33]
	s_waitcnt vmcnt(9)
	v_mfma_f32_16x16x32_bf16 v[42:45], v[82:85], v[50:53], v[42:45]
	v_mfma_f32_16x16x32_bf16 v[46:49], v[66:69], v[50:53], v[46:49]
	s_waitcnt vmcnt(3)
	v_mfma_f32_16x16x32_bf16 v[16:19], v[106:109], v[50:53], v[16:19]
	v_mfma_f32_16x16x32_bf16 v[22:25], v[74:77], v[58:61], v[22:25]
	v_mfma_f32_16x16x32_bf16 v[34:37], v[82:85], v[58:61], v[34:37]
	v_mfma_f32_16x16x32_bf16 v[38:41], v[66:69], v[58:61], v[38:41]
	v_mfma_f32_16x16x32_bf16 v[26:29], v[106:109], v[58:61], v[26:29]
	v_mfma_f32_16x16x32_bf16 v[30:33], v[90:93], v[54:57], v[30:33]
	v_mfma_f32_16x16x32_bf16 v[42:45], v[98:101], v[54:57], v[42:45]
	v_mfma_f32_16x16x32_bf16 v[46:49], v[70:73], v[54:57], v[46:49]
	s_waitcnt vmcnt(1)
	v_mfma_f32_16x16x32_bf16 v[16:19], v[114:117], v[54:57], v[16:19]
	v_mfma_f32_16x16x32_bf16 v[22:25], v[90:93], v[62:65], v[22:25]
	v_mfma_f32_16x16x32_bf16 v[34:37], v[98:101], v[62:65], v[34:37]
	v_mfma_f32_16x16x32_bf16 v[38:41], v[70:73], v[62:65], v[38:41]
	v_mfma_f32_16x16x32_bf16 v[26:29], v[114:117], v[62:65], v[26:29]
	v_mfma_f32_16x16x32_bf16 v[30:33], v[94:97], v[78:81], v[30:33]
	v_mfma_f32_16x16x32_bf16 v[42:45], v[102:105], v[78:81], v[42:45]
	v_mfma_f32_16x16x32_bf16 v[46:49], v[110:113], v[78:81], v[46:49]
	s_waitcnt vmcnt(0)
	v_mfma_f32_16x16x32_bf16 v[16:19], v[118:121], v[78:81], v[16:19]
	v_mfma_f32_16x16x32_bf16 v[22:25], v[94:97], v[86:89], v[22:25]
	v_mfma_f32_16x16x32_bf16 v[34:37], v[102:105], v[86:89], v[34:37]
	v_mfma_f32_16x16x32_bf16 v[38:41], v[110:113], v[86:89], v[38:41]
	v_mfma_f32_16x16x32_bf16 v[26:29], v[118:121], v[86:89], v[26:29]
	ds_write_b128 v14, v[30:33]
	ds_write_b128 v14, v[42:45] offset:64
	ds_write_b128 v14, v[46:49] offset:128
	s_nop 0
	ds_write_b128 v14, v[16:19] offset:192
	ds_write_b128 v14, v[22:25] offset:4096
	ds_write_b128 v14, v[34:37] offset:4160
	ds_write_b128 v14, v[38:41] offset:4224
	ds_write_b128 v14, v[26:29] offset:4288
	s_waitcnt lgkmcnt(0)
	s_barrier
	ds_read_b128 v[16:19], v9
	ds_read_b128 v[22:25], v9 offset:8192
	s_lshl_b32 s24, s11, 7
	v_mov_b32_e32 v5, v20
	s_waitcnt lgkmcnt(0)
	v_pk_add_f32 v[6:7], v[18:19], v[24:25]
	v_pk_add_f32 v[22:23], v[16:17], v[22:23]
	ds_read_b128 v[16:19], v9 offset:16384
	s_waitcnt lgkmcnt(0)
	v_pk_add_f32 v[6:7], v[6:7], v[18:19]
	v_pk_add_f32 v[22:23], v[22:23], v[16:17]
	ds_read_b128 v[16:19], v9 offset:24576
	s_waitcnt lgkmcnt(0)
	v_pk_add_f32 v[6:7], v[6:7], v[18:19]
	v_pk_add_f32 v[22:23], v[22:23], v[16:17]
	ds_read_b128 v[16:19], v9 offset:32768
	s_waitcnt lgkmcnt(0)
	v_pk_add_f32 v[6:7], v[6:7], v[18:19]
	v_pk_add_f32 v[22:23], v[22:23], v[16:17]
	ds_read_b128 v[16:19], v9 offset:40960
	s_waitcnt lgkmcnt(0)
	v_pk_add_f32 v[6:7], v[6:7], v[18:19]
	v_pk_add_f32 v[22:23], v[22:23], v[16:17]
	ds_read_b128 v[16:19], v9 offset:49152
	s_waitcnt lgkmcnt(0)
	v_pk_add_f32 v[6:7], v[6:7], v[18:19]
	v_pk_add_f32 v[22:23], v[22:23], v[16:17]
	ds_read_b128 v[16:19], v9 offset:57344
	s_waitcnt lgkmcnt(0)
	v_pk_add_f32 v[18:19], v[6:7], v[18:19]
	v_add_u32_e32 v6, s4, v8
	v_ashrrev_i32_e32 v7, 31, v6
	v_pk_add_f32 v[16:17], v[22:23], v[16:17]
	v_lshlrev_b64 v[22:23], 11, v[6:7]
	v_lshl_add_u64 v[22:23], s[2:3], 0, v[22:23]
	v_lshl_add_u64 v[22:23], v[22:23], 0, s[24:25]
	v_lshl_add_u64 v[22:23], v[22:23], 0, v[4:5]
	global_load_dwordx2 v[24:25], v[22:23], off
	s_waitcnt vmcnt(0)
	v_lshlrev_b32_e32 v26, 16, v24
	v_and_b32_e32 v27, 0xffff0000, v24
	v_lshlrev_b32_e32 v24, 16, v25
	v_and_b32_e32 v25, 0xffff0000, v25
	v_pk_fma_f32 v[18:19], v[18:19], 0.5, v[24:25] op_sel_hi:[1,0,1]
	v_pk_fma_f32 v[16:17], v[16:17], 0.5, v[26:27] op_sel_hi:[1,0,1]
	v_mul_f32_e32 v15, v19, v19
	v_mul_f32_e32 v5, v17, v17
	v_fmac_f32_e32 v5, v16, v16
	v_fmac_f32_e32 v15, v18, v18
	v_add_f32_e32 v5, v5, v15
	ds_bpermute_b32 v15, v10, v5
	v_cvt_pk_bf16_f32 v24, v16, v17
	v_cvt_pk_bf16_f32 v25, v18, v19
	global_store_dwordx2 v[22:23], v[24:25], off
	s_waitcnt lgkmcnt(0)
	v_add_f32_e32 v5, v5, v15
	ds_bpermute_b32 v15, v11, v5
	s_waitcnt lgkmcnt(0)
	v_add_f32_e32 v5, v5, v15
	ds_bpermute_b32 v15, v12, v5
	s_waitcnt lgkmcnt(0)
	v_add_f32_e32 v5, v5, v15
	ds_bpermute_b32 v15, v13, v5
	s_and_saveexec_b64 s[4:5], s[38:39]
	s_cbranch_execz .LBB0_2089
	v_lshlrev_b64 v[6:7], 6, v[6:7]
	v_lshl_add_u64 v[6:7], s[6:7], 0, v[6:7]
	s_lshl_b32 s24, s11, 2
	s_waitcnt lgkmcnt(0)
	v_add_f32_e32 v5, v5, v15
	v_lshl_add_u64 v[6:7], v[6:7], 0, s[24:25]
	global_store_dword v[6:7], v5, off
	s_branch .LBB0_2089

.LBB0_2099:
	s_waitcnt lgkmcnt(0)
	global_load_dword v3, v20, s[86:87] sc1
	global_load_dword v0, v20, s[86:87] offset:256 sc1
	global_load_dword v1, v20, s[86:87] offset:512 sc1
	global_load_dword v2, v20, s[86:87] offset:768 sc1
	global_load_dword v4, v20, s[86:87] offset:1024 sc1
	global_load_dword v5, v20, s[86:87] offset:1280 sc1
	global_load_dword v6, v20, s[86:87] offset:1536 sc1
	global_load_dword v7, v20, s[86:87] offset:1792 sc1
	global_load_dword v8, v20, s[86:87] offset:2048 sc1
	global_load_dword v9, v20, s[86:87] offset:2304 sc1
	global_load_dword v10, v20, s[86:87] offset:2560 sc1
	global_load_dword v11, v20, s[86:87] offset:2816 sc1
	global_load_dword v12, v20, s[86:87] offset:3072 sc1
	global_load_dword v13, v20, s[86:87] offset:3328 sc1
	global_load_dword v14, v20, s[86:87] offset:3584 sc1
	global_load_dword v15, v20, s[86:87] offset:3840 sc1
	s_mov_b64 s[4:5], -1
	s_mov_b64 s[2:3], -1
	s_waitcnt vmcnt(0)
	v_add_u32_e32 v16, v0, v3
	v_add_u32_e32 v16, v16, v1
	v_add_u32_e32 v16, v16, v2
	v_add_u32_e32 v16, v16, v4
	v_add_u32_e32 v16, v16, v5
	v_add_u32_e32 v16, v16, v6
	v_add_u32_e32 v16, v16, v7
	v_add_u32_e32 v16, v16, v8
	v_add_u32_e32 v16, v16, v9
	v_add_u32_e32 v16, v16, v10
	v_add_u32_e32 v16, v16, v11
	v_add_u32_e32 v16, v16, v12
	v_add_u32_e32 v16, v16, v13
	v_add_u32_e32 v16, v16, v14
	v_add_u32_e32 v16, v16, v15
	v_cmp_eq_u32_e32 vcc, s81, v16
	s_cbranch_vccnz .LBB0_2098
	s_and_b32 s2, s8, 0xff
	s_cmp_eq_u32 s2, 0
	s_mov_b64 s[2:3], -1
	s_mov_b64 s[6:7], -1
	s_sleep 1
	s_cbranch_scc1 .LBB0_2103
	s_and_b64 vcc, exec, s[6:7]
	s_cbranch_vccz .LBB0_2098
